# instruction selection: packed f32 (v_pk_mul/v_pk_add) for sigmoid pre/post ops in the in-proj gate-tile epilogue
# speedup vs baseline: 1.0095x; 1.0050x over previous
; __device__ __forceinline__ unsigned pk2(float lo, float hi) { f32x2 v = {lo, hi}; bf16x2_t b = __builtin_convertvector(v, bf16x2_t); return __builtin_bit_cast(unsigned, b); }
; __device__ __forceinline__ float fast_exp(float x) { return __builtin_amdgcn_exp2f(x * 1.4426950408889634f); }
; __device__ __forceinline__ float fast_rcp(float x) { return __builtin_amdgcn_rcpf(x); }
; __device__ __forceinline__ float sigmoidf_(float x) { return fast_rcp(1.f + fast_exp(-x)); }
;     __device__ __forceinline__ void operator()(const f32x4 (&acc)[2][2][4][2], const Unit& u, int wr, int wc, int fr, int fq) const {
;     ...
;             const int col0 = u.pn * 256 + wc * 32 + 8 * fq;
; #pragma unroll
;             for (int ai = 0; ai < 2; ++ai)
; #pragma unroll
;                 for (int m = 0; m < 4; ++m) {
;                     bf16_t* rowp = P + (size_t)(row0 + ai * 128 + m * 16) * PS + col0;
; #pragma unroll
;                     for (int bj = 0; bj < 2; ++bj) {
;                         f32x4 v0 = acc[ai][bj][m][0], v1 = acc[ai][bj][m][1];
;                         if (sg) {
; #pragma unroll
;                             for (int e = 0; e < 4; ++e) { v0[e] = sigmoidf_(v0[e]); v1[e] = sigmoidf_(v1[e]); }
;                         }
;                         u32x4 w; w.x = pk2(v0[0], v0[1]); w.y = pk2(v0[2], v0[3]); w.z = pk2(v1[0], v1[1]); w.w = pk2(v1[2], v1[3]);
;                         *(u32x4*)(rowp + bj * 128) = w;
.LBB0_339:
	s_cmp_gt_i32 s40, 23
	s_cselect_b64 s[6:7], -1, 0
	s_cmp_lt_i32 s40, 24
	s_cbranch_scc1 .LBB0_341
	v_pk_mul_f32 v[128:129], v[128:129], s[90:91] op_sel:[0,1]
	v_pk_mul_f32 v[124:125], v[124:125], s[90:91] op_sel:[0,1]
	v_pk_mul_f32 v[130:131], v[130:131], s[90:91] op_sel:[0,1]
	v_pk_mul_f32 v[126:127], v[126:127], s[90:91] op_sel:[0,1]
	v_exp_f32_e32 v128, v128
	v_exp_f32_e32 v124, v124
	v_exp_f32_e32 v129, v129
	v_exp_f32_e32 v125, v125
	v_exp_f32_e32 v130, v130
	v_exp_f32_e32 v126, v126
	v_exp_f32_e32 v131, v131
	v_exp_f32_e32 v127, v127
	v_pk_add_f32 v[128:129], v[128:129], 1.0 op_sel_hi:[1,0]
	v_pk_add_f32 v[124:125], v[124:125], 1.0 op_sel_hi:[1,0]
	v_pk_add_f32 v[130:131], v[130:131], 1.0 op_sel_hi:[1,0]
	v_pk_add_f32 v[126:127], v[126:127], 1.0 op_sel_hi:[1,0]
	v_rcp_f32_e32 v128, v128
	v_rcp_f32_e32 v124, v124
	v_rcp_f32_e32 v129, v129
	v_rcp_f32_e32 v125, v125
	v_rcp_f32_e32 v130, v130
	v_rcp_f32_e32 v126, v126
	v_rcp_f32_e32 v131, v131
	v_rcp_f32_e32 v127, v127
.LBB0_341:
	v_lshl_or_b32 v150, s40, 8, v156
	v_mov_b64_e32 v[152:153], s[8:9]
	v_ashrrev_i32_e32 v151, 31, v150
	v_mad_i64_i32 v[152:153], s[40:41], v142, s90, v[152:153]
	v_cvt_pk_bf16_f32 v128, v128, v129
	v_cvt_pk_bf16_f32 v129, v130, v131
	v_cvt_pk_bf16_f32 v130, v124, v125
	v_cndmask_b32_e64 v124, 0, 1, s[6:7]
	v_lshl_add_u64 v[152:153], v[150:151], 1, v[152:153]
	v_cvt_pk_bf16_f32 v131, v126, v127
	v_cmp_ne_u32_e64 s[40:41], 1, v124
	s_andn2_b64 vcc, exec, s[6:7]
	global_store_dwordx4 v[152:153], v[128:131], off
	s_cbranch_vccnz .LBB0_343
	v_pk_mul_f32 v[120:121], v[120:121], s[90:91] op_sel:[0,1]
	v_pk_mul_f32 v[116:117], v[116:117], s[90:91] op_sel:[0,1]
	v_pk_mul_f32 v[122:123], v[122:123], s[90:91] op_sel:[0,1]
	v_pk_mul_f32 v[118:119], v[118:119], s[90:91] op_sel:[0,1]
	v_exp_f32_e32 v120, v120
	v_exp_f32_e32 v116, v116
	v_exp_f32_e32 v121, v121
	v_exp_f32_e32 v117, v117
	v_exp_f32_e32 v122, v122
	v_exp_f32_e32 v118, v118
	v_exp_f32_e32 v123, v123
	v_exp_f32_e32 v119, v119
	v_pk_add_f32 v[120:121], v[120:121], 1.0 op_sel_hi:[1,0]
	v_pk_add_f32 v[116:117], v[116:117], 1.0 op_sel_hi:[1,0]
	v_pk_add_f32 v[122:123], v[122:123], 1.0 op_sel_hi:[1,0]
	v_pk_add_f32 v[118:119], v[118:119], 1.0 op_sel_hi:[1,0]
	v_rcp_f32_e32 v120, v120
	v_rcp_f32_e32 v116, v116
	v_rcp_f32_e32 v121, v121
	v_rcp_f32_e32 v117, v117
	v_rcp_f32_e32 v122, v122
	v_rcp_f32_e32 v118, v118
	v_rcp_f32_e32 v123, v123
	v_rcp_f32_e32 v119, v119
.LBB0_343:
	v_cvt_pk_bf16_f32 v120, v120, v121
	v_cvt_pk_bf16_f32 v121, v122, v123
	v_cvt_pk_bf16_f32 v122, v116, v117
	v_cvt_pk_bf16_f32 v123, v118, v119
	s_and_b64 vcc, exec, s[40:41]
	global_store_dwordx4 v[152:153], v[120:123], off offset:256
	s_cbranch_vccnz .LBB0_345
	v_pk_mul_f32 v[112:113], v[112:113], s[90:91] op_sel:[0,1]
	v_pk_mul_f32 v[108:109], v[108:109], s[90:91] op_sel:[0,1]
	v_pk_mul_f32 v[114:115], v[114:115], s[90:91] op_sel:[0,1]
	v_pk_mul_f32 v[110:111], v[110:111], s[90:91] op_sel:[0,1]
	v_exp_f32_e32 v112, v112
	v_exp_f32_e32 v108, v108
	v_exp_f32_e32 v113, v113
	v_exp_f32_e32 v109, v109
	v_exp_f32_e32 v114, v114
	v_exp_f32_e32 v110, v110
	v_exp_f32_e32 v115, v115
	v_exp_f32_e32 v111, v111
	v_pk_add_f32 v[112:113], v[112:113], 1.0 op_sel_hi:[1,0]
	v_pk_add_f32 v[108:109], v[108:109], 1.0 op_sel_hi:[1,0]
	v_pk_add_f32 v[114:115], v[114:115], 1.0 op_sel_hi:[1,0]
	v_pk_add_f32 v[110:111], v[110:111], 1.0 op_sel_hi:[1,0]
	v_rcp_f32_e32 v112, v112
	v_rcp_f32_e32 v108, v108
	v_rcp_f32_e32 v113, v113
	v_rcp_f32_e32 v109, v109
	v_rcp_f32_e32 v114, v114
	v_rcp_f32_e32 v110, v110
	v_rcp_f32_e32 v115, v115
	v_rcp_f32_e32 v111, v111
.LBB0_345:
	v_or_b32_e32 v118, 16, v142
	v_mov_b64_e32 v[116:117], s[8:9]
	v_mad_i64_i32 v[116:117], s[6:7], v118, s90, v[116:117]
	v_lshl_add_u64 v[116:117], v[150:151], 1, v[116:117]
	v_cvt_pk_bf16_f32 v112, v112, v113
	v_cvt_pk_bf16_f32 v113, v114, v115
	v_cvt_pk_bf16_f32 v114, v108, v109
	v_cvt_pk_bf16_f32 v115, v110, v111
	s_and_b64 vcc, exec, s[40:41]
	global_store_dwordx4 v[116:117], v[112:115], off
	s_cbranch_vccnz .LBB0_347
	v_pk_mul_f32 v[104:105], v[104:105], s[90:91] op_sel:[0,1]
	v_pk_mul_f32 v[100:101], v[100:101], s[90:91] op_sel:[0,1]
	v_pk_mul_f32 v[106:107], v[106:107], s[90:91] op_sel:[0,1]
	v_pk_mul_f32 v[102:103], v[102:103], s[90:91] op_sel:[0,1]
	v_exp_f32_e32 v104, v104
	v_exp_f32_e32 v100, v100
	v_exp_f32_e32 v105, v105
	v_exp_f32_e32 v101, v101
	v_exp_f32_e32 v106, v106
	v_exp_f32_e32 v102, v102
	v_exp_f32_e32 v107, v107
	v_exp_f32_e32 v103, v103
	v_pk_add_f32 v[104:105], v[104:105], 1.0 op_sel_hi:[1,0]
	v_pk_add_f32 v[100:101], v[100:101], 1.0 op_sel_hi:[1,0]
	v_pk_add_f32 v[106:107], v[106:107], 1.0 op_sel_hi:[1,0]
	v_pk_add_f32 v[102:103], v[102:103], 1.0 op_sel_hi:[1,0]
	v_rcp_f32_e32 v104, v104
	v_rcp_f32_e32 v100, v100
	v_rcp_f32_e32 v105, v105
	v_rcp_f32_e32 v101, v101
	v_rcp_f32_e32 v106, v106
	v_rcp_f32_e32 v102, v102
	v_rcp_f32_e32 v107, v107
	v_rcp_f32_e32 v103, v103
.LBB0_347:
	v_cvt_pk_bf16_f32 v104, v104, v105
	v_cvt_pk_bf16_f32 v105, v106, v107
	v_cvt_pk_bf16_f32 v106, v100, v101
	v_cvt_pk_bf16_f32 v107, v102, v103
	s_and_b64 vcc, exec, s[40:41]
	global_store_dwordx4 v[116:117], v[104:107], off offset:256
	s_cbranch_vccnz .LBB0_349
	v_pk_mul_f32 v[96:97], v[96:97], s[90:91] op_sel:[0,1]
	v_pk_mul_f32 v[92:93], v[92:93], s[90:91] op_sel:[0,1]
	v_pk_mul_f32 v[98:99], v[98:99], s[90:91] op_sel:[0,1]
	v_pk_mul_f32 v[94:95], v[94:95], s[90:91] op_sel:[0,1]
	v_exp_f32_e32 v96, v96
	v_exp_f32_e32 v92, v92
	v_exp_f32_e32 v97, v97
	v_exp_f32_e32 v93, v93
	v_exp_f32_e32 v98, v98
	v_exp_f32_e32 v94, v94
	v_exp_f32_e32 v99, v99
	v_exp_f32_e32 v95, v95
	v_pk_add_f32 v[96:97], v[96:97], 1.0 op_sel_hi:[1,0]
	v_pk_add_f32 v[92:93], v[92:93], 1.0 op_sel_hi:[1,0]
	v_pk_add_f32 v[98:99], v[98:99], 1.0 op_sel_hi:[1,0]
	v_pk_add_f32 v[94:95], v[94:95], 1.0 op_sel_hi:[1,0]
	v_rcp_f32_e32 v96, v96
	v_rcp_f32_e32 v92, v92
	v_rcp_f32_e32 v97, v97
	v_rcp_f32_e32 v93, v93
	v_rcp_f32_e32 v98, v98
	v_rcp_f32_e32 v94, v94
	v_rcp_f32_e32 v99, v99
	v_rcp_f32_e32 v95, v95
; __device__ __forceinline__ unsigned pk2(float lo, float hi) { f32x2 v = {lo, hi}; bf16x2_t b = __builtin_convertvector(v, bf16x2_t); return __builtin_bit_cast(unsigned, b); }
; __device__ __forceinline__ float fast_exp(float x) { return __builtin_amdgcn_exp2f(x * 1.4426950408889634f); }
; __device__ __forceinline__ float fast_rcp(float x) { return __builtin_amdgcn_rcpf(x); }
; __device__ __forceinline__ float sigmoidf_(float x) { return fast_rcp(1.f + fast_exp(-x)); }
;     __device__ __forceinline__ void operator()(const f32x4 (&acc)[2][2][4][2], const Unit& u, int wr, int wc, int fr, int fq) const {
;     ...
;             for (int ai = 0; ai < 2; ++ai)
; #pragma unroll
;                 for (int m = 0; m < 4; ++m) {
;                     bf16_t* rowp = P + (size_t)(row0 + ai * 128 + m * 16) * PS + col0;
; #pragma unroll
;                     for (int bj = 0; bj < 2; ++bj) {
;                         f32x4 v0 = acc[ai][bj][m][0], v1 = acc[ai][bj][m][1];
;                         if (sg) {
; #pragma unroll
;                             for (int e = 0; e < 4; ++e) { v0[e] = sigmoidf_(v0[e]); v1[e] = sigmoidf_(v1[e]); }
;                         }
;                         u32x4 w; w.x = pk2(v0[0], v0[1]); w.y = pk2(v0[2], v0[3]); w.z = pk2(v1[0], v1[1]); w.w = pk2(v1[2], v1[3]);
;                         *(u32x4*)(rowp + bj * 128) = w;
.LBB0_349:
	v_or_b32_e32 v102, 32, v142
	v_mov_b64_e32 v[100:101], s[8:9]
	v_mad_i64_i32 v[100:101], s[6:7], v102, s90, v[100:101]
	v_lshl_add_u64 v[100:101], v[150:151], 1, v[100:101]
	v_cvt_pk_bf16_f32 v96, v96, v97
	v_cvt_pk_bf16_f32 v97, v98, v99
	v_cvt_pk_bf16_f32 v98, v92, v93
	v_cvt_pk_bf16_f32 v99, v94, v95
	s_and_b64 vcc, exec, s[40:41]
	global_store_dwordx4 v[100:101], v[96:99], off
	s_cbranch_vccnz .LBB0_351
	v_pk_mul_f32 v[88:89], v[88:89], s[90:91] op_sel:[0,1]
	v_pk_mul_f32 v[84:85], v[84:85], s[90:91] op_sel:[0,1]
	v_pk_mul_f32 v[90:91], v[90:91], s[90:91] op_sel:[0,1]
	v_pk_mul_f32 v[86:87], v[86:87], s[90:91] op_sel:[0,1]
	v_exp_f32_e32 v88, v88
	v_exp_f32_e32 v84, v84
	v_exp_f32_e32 v89, v89
	v_exp_f32_e32 v85, v85
	v_exp_f32_e32 v90, v90
	v_exp_f32_e32 v86, v86
	v_exp_f32_e32 v91, v91
	v_exp_f32_e32 v87, v87
	v_pk_add_f32 v[88:89], v[88:89], 1.0 op_sel_hi:[1,0]
	v_pk_add_f32 v[84:85], v[84:85], 1.0 op_sel_hi:[1,0]
	v_pk_add_f32 v[90:91], v[90:91], 1.0 op_sel_hi:[1,0]
	v_pk_add_f32 v[86:87], v[86:87], 1.0 op_sel_hi:[1,0]
	v_rcp_f32_e32 v88, v88
	v_rcp_f32_e32 v84, v84
	v_rcp_f32_e32 v89, v89
	v_rcp_f32_e32 v85, v85
	v_rcp_f32_e32 v90, v90
	v_rcp_f32_e32 v86, v86
	v_rcp_f32_e32 v91, v91
	v_rcp_f32_e32 v87, v87
.LBB0_351:
	v_cvt_pk_bf16_f32 v88, v88, v89
	v_cvt_pk_bf16_f32 v89, v90, v91
	v_cvt_pk_bf16_f32 v90, v84, v85
	v_cvt_pk_bf16_f32 v91, v86, v87
	s_and_b64 vcc, exec, s[40:41]
	global_store_dwordx4 v[100:101], v[88:91], off offset:256
	s_cbranch_vccnz .LBB0_353
	v_pk_mul_f32 v[80:81], v[80:81], s[90:91] op_sel:[0,1]
	v_pk_mul_f32 v[76:77], v[76:77], s[90:91] op_sel:[0,1]
	v_pk_mul_f32 v[82:83], v[82:83], s[90:91] op_sel:[0,1]
	v_pk_mul_f32 v[78:79], v[78:79], s[90:91] op_sel:[0,1]
	v_exp_f32_e32 v80, v80
	v_exp_f32_e32 v76, v76
	v_exp_f32_e32 v81, v81
	v_exp_f32_e32 v77, v77
	v_exp_f32_e32 v82, v82
	v_exp_f32_e32 v78, v78
	v_exp_f32_e32 v83, v83
	v_exp_f32_e32 v79, v79
	v_pk_add_f32 v[80:81], v[80:81], 1.0 op_sel_hi:[1,0]
	v_pk_add_f32 v[76:77], v[76:77], 1.0 op_sel_hi:[1,0]
	v_pk_add_f32 v[82:83], v[82:83], 1.0 op_sel_hi:[1,0]
	v_pk_add_f32 v[78:79], v[78:79], 1.0 op_sel_hi:[1,0]
	v_rcp_f32_e32 v80, v80
	v_rcp_f32_e32 v76, v76
	v_rcp_f32_e32 v81, v81
	v_rcp_f32_e32 v77, v77
	v_rcp_f32_e32 v82, v82
	v_rcp_f32_e32 v78, v78
	v_rcp_f32_e32 v83, v83
	v_rcp_f32_e32 v79, v79
.LBB0_353:
	v_or_b32_e32 v86, 48, v142
	v_mov_b64_e32 v[84:85], s[8:9]
	v_mad_i64_i32 v[84:85], s[6:7], v86, s90, v[84:85]
	v_lshl_add_u64 v[84:85], v[150:151], 1, v[84:85]
	v_cvt_pk_bf16_f32 v80, v80, v81
	v_cvt_pk_bf16_f32 v81, v82, v83
	v_cvt_pk_bf16_f32 v82, v76, v77
	v_cvt_pk_bf16_f32 v83, v78, v79
	s_and_b64 vcc, exec, s[40:41]
	global_store_dwordx4 v[84:85], v[80:83], off
	s_cbranch_vccnz .LBB0_355
	v_pk_mul_f32 v[72:73], v[72:73], s[90:91] op_sel:[0,1]
	v_pk_mul_f32 v[68:69], v[68:69], s[90:91] op_sel:[0,1]
	v_pk_mul_f32 v[74:75], v[74:75], s[90:91] op_sel:[0,1]
	v_pk_mul_f32 v[70:71], v[70:71], s[90:91] op_sel:[0,1]
	v_exp_f32_e32 v72, v72
	v_exp_f32_e32 v68, v68
	v_exp_f32_e32 v73, v73
	v_exp_f32_e32 v69, v69
	v_exp_f32_e32 v74, v74
	v_exp_f32_e32 v70, v70
	v_exp_f32_e32 v75, v75
	v_exp_f32_e32 v71, v71
	v_pk_add_f32 v[72:73], v[72:73], 1.0 op_sel_hi:[1,0]
	v_pk_add_f32 v[68:69], v[68:69], 1.0 op_sel_hi:[1,0]
	v_pk_add_f32 v[74:75], v[74:75], 1.0 op_sel_hi:[1,0]
	v_pk_add_f32 v[70:71], v[70:71], 1.0 op_sel_hi:[1,0]
	v_rcp_f32_e32 v72, v72
	v_rcp_f32_e32 v68, v68
	v_rcp_f32_e32 v73, v73
	v_rcp_f32_e32 v69, v69
	v_rcp_f32_e32 v74, v74
	v_rcp_f32_e32 v70, v70
	v_rcp_f32_e32 v75, v75
	v_rcp_f32_e32 v71, v71
.LBB0_355:
	v_cvt_pk_bf16_f32 v72, v72, v73
	v_cvt_pk_bf16_f32 v73, v74, v75
	v_cvt_pk_bf16_f32 v74, v68, v69
	v_cvt_pk_bf16_f32 v75, v70, v71
	s_and_b64 vcc, exec, s[40:41]
	global_store_dwordx4 v[84:85], v[72:75], off offset:256
	s_cbranch_vccnz .LBB0_357
	v_pk_mul_f32 v[64:65], v[64:65], s[90:91] op_sel:[0,1]
	v_pk_mul_f32 v[60:61], v[60:61], s[90:91] op_sel:[0,1]
	v_pk_mul_f32 v[66:67], v[66:67], s[90:91] op_sel:[0,1]
	v_pk_mul_f32 v[62:63], v[62:63], s[90:91] op_sel:[0,1]
	v_exp_f32_e32 v64, v64
	v_exp_f32_e32 v60, v60
	v_exp_f32_e32 v65, v65
	v_exp_f32_e32 v61, v61
	v_exp_f32_e32 v66, v66
	v_exp_f32_e32 v62, v62
	v_exp_f32_e32 v67, v67
	v_exp_f32_e32 v63, v63
	v_pk_add_f32 v[64:65], v[64:65], 1.0 op_sel_hi:[1,0]
	v_pk_add_f32 v[60:61], v[60:61], 1.0 op_sel_hi:[1,0]
	v_pk_add_f32 v[66:67], v[66:67], 1.0 op_sel_hi:[1,0]
	v_pk_add_f32 v[62:63], v[62:63], 1.0 op_sel_hi:[1,0]
	v_rcp_f32_e32 v64, v64
	v_rcp_f32_e32 v60, v60
	v_rcp_f32_e32 v65, v65
	v_rcp_f32_e32 v61, v61
	v_rcp_f32_e32 v66, v66
	v_rcp_f32_e32 v62, v62
	v_rcp_f32_e32 v67, v67
	v_rcp_f32_e32 v63, v63
.LBB0_357:
	v_add_u32_e32 v70, 0x80, v142
	v_mov_b64_e32 v[68:69], s[8:9]
	v_mad_i64_i32 v[68:69], s[6:7], v70, s90, v[68:69]
	v_lshl_add_u64 v[68:69], v[150:151], 1, v[68:69]
	v_cvt_pk_bf16_f32 v64, v64, v65
	v_cvt_pk_bf16_f32 v65, v66, v67
	v_cvt_pk_bf16_f32 v66, v60, v61
	v_cvt_pk_bf16_f32 v67, v62, v63
	s_and_b64 vcc, exec, s[40:41]
	global_store_dwordx4 v[68:69], v[64:67], off
	s_cbranch_vccnz .LBB0_359
	v_pk_mul_f32 v[56:57], v[56:57], s[90:91] op_sel:[0,1]
	v_pk_mul_f32 v[52:53], v[52:53], s[90:91] op_sel:[0,1]
	v_pk_mul_f32 v[58:59], v[58:59], s[90:91] op_sel:[0,1]
	v_pk_mul_f32 v[54:55], v[54:55], s[90:91] op_sel:[0,1]
	v_exp_f32_e32 v56, v56
	v_exp_f32_e32 v52, v52
	v_exp_f32_e32 v57, v57
	v_exp_f32_e32 v53, v53
	v_exp_f32_e32 v58, v58
	v_exp_f32_e32 v54, v54
	v_exp_f32_e32 v59, v59
	v_exp_f32_e32 v55, v55
	v_pk_add_f32 v[56:57], v[56:57], 1.0 op_sel_hi:[1,0]
	v_pk_add_f32 v[52:53], v[52:53], 1.0 op_sel_hi:[1,0]
	v_pk_add_f32 v[58:59], v[58:59], 1.0 op_sel_hi:[1,0]
	v_pk_add_f32 v[54:55], v[54:55], 1.0 op_sel_hi:[1,0]
	v_rcp_f32_e32 v56, v56
	v_rcp_f32_e32 v52, v52
	v_rcp_f32_e32 v57, v57
	v_rcp_f32_e32 v53, v53
	v_rcp_f32_e32 v58, v58
	v_rcp_f32_e32 v54, v54
	v_rcp_f32_e32 v59, v59
	v_rcp_f32_e32 v55, v55
; __device__ __forceinline__ unsigned pk2(float lo, float hi) { f32x2 v = {lo, hi}; bf16x2_t b = __builtin_convertvector(v, bf16x2_t); return __builtin_bit_cast(unsigned, b); }
; __device__ __forceinline__ float fast_exp(float x) { return __builtin_amdgcn_exp2f(x * 1.4426950408889634f); }
; __device__ __forceinline__ float fast_rcp(float x) { return __builtin_amdgcn_rcpf(x); }
; __device__ __forceinline__ float sigmoidf_(float x) { return fast_rcp(1.f + fast_exp(-x)); }
;     __device__ __forceinline__ void operator()(const f32x4 (&acc)[2][2][4][2], const Unit& u, int wr, int wc, int fr, int fq) const {
;     ...
;             for (int ai = 0; ai < 2; ++ai)
; #pragma unroll
;                 for (int m = 0; m < 4; ++m) {
;                     bf16_t* rowp = P + (size_t)(row0 + ai * 128 + m * 16) * PS + col0;
; #pragma unroll
;                     for (int bj = 0; bj < 2; ++bj) {
;                         f32x4 v0 = acc[ai][bj][m][0], v1 = acc[ai][bj][m][1];
;                         if (sg) {
; #pragma unroll
;                             for (int e = 0; e < 4; ++e) { v0[e] = sigmoidf_(v0[e]); v1[e] = sigmoidf_(v1[e]); }
;                         }
;                         u32x4 w; w.x = pk2(v0[0], v0[1]); w.y = pk2(v0[2], v0[3]); w.z = pk2(v1[0], v1[1]); w.w = pk2(v1[2], v1[3]);
;                         *(u32x4*)(rowp + bj * 128) = w;
.LBB0_359:
	v_cvt_pk_bf16_f32 v56, v56, v57
	v_cvt_pk_bf16_f32 v57, v58, v59
	v_cvt_pk_bf16_f32 v58, v52, v53
	v_cvt_pk_bf16_f32 v59, v54, v55
	s_and_b64 vcc, exec, s[40:41]
	global_store_dwordx4 v[68:69], v[56:59], off offset:256
	s_cbranch_vccnz .LBB0_361
	v_pk_mul_f32 v[48:49], v[48:49], s[90:91] op_sel:[0,1]
	v_pk_mul_f32 v[44:45], v[44:45], s[90:91] op_sel:[0,1]
	v_pk_mul_f32 v[50:51], v[50:51], s[90:91] op_sel:[0,1]
	v_pk_mul_f32 v[46:47], v[46:47], s[90:91] op_sel:[0,1]
	v_exp_f32_e32 v48, v48
	v_exp_f32_e32 v44, v44
	v_exp_f32_e32 v49, v49
	v_exp_f32_e32 v45, v45
	v_exp_f32_e32 v50, v50
	v_exp_f32_e32 v46, v46
	v_exp_f32_e32 v51, v51
	v_exp_f32_e32 v47, v47
	v_pk_add_f32 v[48:49], v[48:49], 1.0 op_sel_hi:[1,0]
	v_pk_add_f32 v[44:45], v[44:45], 1.0 op_sel_hi:[1,0]
	v_pk_add_f32 v[50:51], v[50:51], 1.0 op_sel_hi:[1,0]
	v_pk_add_f32 v[46:47], v[46:47], 1.0 op_sel_hi:[1,0]
	v_rcp_f32_e32 v48, v48
	v_rcp_f32_e32 v44, v44
	v_rcp_f32_e32 v49, v49
	v_rcp_f32_e32 v45, v45
	v_rcp_f32_e32 v50, v50
	v_rcp_f32_e32 v46, v46
	v_rcp_f32_e32 v51, v51
	v_rcp_f32_e32 v47, v47
.LBB0_361:
	v_add_u32_e32 v54, 0x90, v142
	v_mov_b64_e32 v[52:53], s[8:9]
	v_mad_i64_i32 v[52:53], s[6:7], v54, s90, v[52:53]
	v_lshl_add_u64 v[52:53], v[150:151], 1, v[52:53]
	v_cvt_pk_bf16_f32 v48, v48, v49
	v_cvt_pk_bf16_f32 v49, v50, v51
	v_cvt_pk_bf16_f32 v50, v44, v45
	v_cvt_pk_bf16_f32 v51, v46, v47
	s_and_b64 vcc, exec, s[40:41]
	global_store_dwordx4 v[52:53], v[48:51], off
	s_cbranch_vccnz .LBB0_363
	v_pk_mul_f32 v[40:41], v[40:41], s[90:91] op_sel:[0,1]
	v_pk_mul_f32 v[36:37], v[36:37], s[90:91] op_sel:[0,1]
	v_pk_mul_f32 v[42:43], v[42:43], s[90:91] op_sel:[0,1]
	v_pk_mul_f32 v[38:39], v[38:39], s[90:91] op_sel:[0,1]
	v_exp_f32_e32 v40, v40
	v_exp_f32_e32 v36, v36
	v_exp_f32_e32 v41, v41
	v_exp_f32_e32 v37, v37
	v_exp_f32_e32 v42, v42
	v_exp_f32_e32 v38, v38
	v_exp_f32_e32 v43, v43
	v_exp_f32_e32 v39, v39
	v_pk_add_f32 v[40:41], v[40:41], 1.0 op_sel_hi:[1,0]
	v_pk_add_f32 v[36:37], v[36:37], 1.0 op_sel_hi:[1,0]
	v_pk_add_f32 v[42:43], v[42:43], 1.0 op_sel_hi:[1,0]
	v_pk_add_f32 v[38:39], v[38:39], 1.0 op_sel_hi:[1,0]
	v_rcp_f32_e32 v40, v40
	v_rcp_f32_e32 v36, v36
	v_rcp_f32_e32 v41, v41
	v_rcp_f32_e32 v37, v37
	v_rcp_f32_e32 v42, v42
	v_rcp_f32_e32 v38, v38
	v_rcp_f32_e32 v43, v43
	v_rcp_f32_e32 v39, v39
.LBB0_363:
	v_cvt_pk_bf16_f32 v40, v40, v41
	v_cvt_pk_bf16_f32 v41, v42, v43
	v_cvt_pk_bf16_f32 v42, v36, v37
	v_cvt_pk_bf16_f32 v43, v38, v39
	s_and_b64 vcc, exec, s[40:41]
	global_store_dwordx4 v[52:53], v[40:43], off offset:256
	s_cbranch_vccnz .LBB0_365
	v_pk_mul_f32 v[28:29], v[28:29], s[90:91] op_sel:[0,1]
	v_pk_mul_f32 v[24:25], v[24:25], s[90:91] op_sel:[0,1]
	v_pk_mul_f32 v[30:31], v[30:31], s[90:91] op_sel:[0,1]
	v_pk_mul_f32 v[26:27], v[26:27], s[90:91] op_sel:[0,1]
	v_exp_f32_e32 v28, v28
	v_exp_f32_e32 v24, v24
	v_exp_f32_e32 v29, v29
	v_exp_f32_e32 v25, v25
	v_exp_f32_e32 v30, v30
	v_exp_f32_e32 v26, v26
	v_exp_f32_e32 v31, v31
	v_exp_f32_e32 v27, v27
	v_pk_add_f32 v[28:29], v[28:29], 1.0 op_sel_hi:[1,0]
	v_pk_add_f32 v[24:25], v[24:25], 1.0 op_sel_hi:[1,0]
	v_pk_add_f32 v[30:31], v[30:31], 1.0 op_sel_hi:[1,0]
	v_pk_add_f32 v[26:27], v[26:27], 1.0 op_sel_hi:[1,0]
	v_rcp_f32_e32 v28, v28
	v_rcp_f32_e32 v24, v24
	v_rcp_f32_e32 v29, v29
	v_rcp_f32_e32 v25, v25
	v_rcp_f32_e32 v30, v30
	v_rcp_f32_e32 v26, v26
	v_rcp_f32_e32 v31, v31
	v_rcp_f32_e32 v27, v27
.LBB0_365:
	v_add_u32_e32 v38, 0xa0, v142
	v_mov_b64_e32 v[36:37], s[8:9]
	v_mad_i64_i32 v[36:37], s[6:7], v38, s90, v[36:37]
	v_lshl_add_u64 v[36:37], v[150:151], 1, v[36:37]
	v_cvt_pk_bf16_f32 v28, v28, v29
	v_cvt_pk_bf16_f32 v29, v30, v31
	v_cvt_pk_bf16_f32 v30, v24, v25
	v_cvt_pk_bf16_f32 v31, v26, v27
	s_and_b64 vcc, exec, s[40:41]
	global_store_dwordx4 v[36:37], v[28:31], off
	s_cbranch_vccnz .LBB0_367
	v_pk_mul_f32 v[20:21], v[20:21], s[90:91] op_sel:[0,1]
	v_pk_mul_f32 v[16:17], v[16:17], s[90:91] op_sel:[0,1]
	v_pk_mul_f32 v[22:23], v[22:23], s[90:91] op_sel:[0,1]
	v_pk_mul_f32 v[18:19], v[18:19], s[90:91] op_sel:[0,1]
	v_exp_f32_e32 v20, v20
	v_exp_f32_e32 v16, v16
	v_exp_f32_e32 v21, v21
	v_exp_f32_e32 v17, v17
	v_exp_f32_e32 v22, v22
	v_exp_f32_e32 v18, v18
	v_exp_f32_e32 v23, v23
	v_exp_f32_e32 v19, v19
	v_pk_add_f32 v[20:21], v[20:21], 1.0 op_sel_hi:[1,0]
	v_pk_add_f32 v[16:17], v[16:17], 1.0 op_sel_hi:[1,0]
	v_pk_add_f32 v[22:23], v[22:23], 1.0 op_sel_hi:[1,0]
	v_pk_add_f32 v[18:19], v[18:19], 1.0 op_sel_hi:[1,0]
	v_rcp_f32_e32 v20, v20
	v_rcp_f32_e32 v16, v16
	v_rcp_f32_e32 v21, v21
	v_rcp_f32_e32 v17, v17
	v_rcp_f32_e32 v22, v22
	v_rcp_f32_e32 v18, v18
	v_rcp_f32_e32 v23, v23
	v_rcp_f32_e32 v19, v19
.LBB0_367:
	v_cvt_pk_bf16_f32 v20, v20, v21
	v_cvt_pk_bf16_f32 v21, v22, v23
	v_cvt_pk_bf16_f32 v22, v16, v17
	v_cvt_pk_bf16_f32 v23, v18, v19
	s_and_b64 vcc, exec, s[40:41]
	global_store_dwordx4 v[36:37], v[20:23], off offset:256
	s_cbranch_vccnz .LBB0_369
	v_pk_mul_f32 v[12:13], v[12:13], s[90:91] op_sel:[0,1]
	v_pk_mul_f32 v[8:9], v[8:9], s[90:91] op_sel:[0,1]
	v_pk_mul_f32 v[14:15], v[14:15], s[90:91] op_sel:[0,1]
	v_pk_mul_f32 v[10:11], v[10:11], s[90:91] op_sel:[0,1]
	v_exp_f32_e32 v12, v12
	v_exp_f32_e32 v8, v8
	v_exp_f32_e32 v13, v13
	v_exp_f32_e32 v9, v9
	v_exp_f32_e32 v14, v14
	v_exp_f32_e32 v10, v10
	v_exp_f32_e32 v15, v15
	v_exp_f32_e32 v11, v11
	v_pk_add_f32 v[12:13], v[12:13], 1.0 op_sel_hi:[1,0]
	v_pk_add_f32 v[8:9], v[8:9], 1.0 op_sel_hi:[1,0]
	v_pk_add_f32 v[14:15], v[14:15], 1.0 op_sel_hi:[1,0]
	v_pk_add_f32 v[10:11], v[10:11], 1.0 op_sel_hi:[1,0]
	v_rcp_f32_e32 v12, v12
	v_rcp_f32_e32 v8, v8
	v_rcp_f32_e32 v13, v13
	v_rcp_f32_e32 v9, v9
	v_rcp_f32_e32 v14, v14
	v_rcp_f32_e32 v10, v10
	v_rcp_f32_e32 v15, v15
	v_rcp_f32_e32 v11, v11
.LBB0_369:
	v_add_u32_e32 v18, 0xb0, v142
	v_mov_b64_e32 v[16:17], s[8:9]
	v_mad_i64_i32 v[16:17], s[6:7], v18, s90, v[16:17]
	v_lshl_add_u64 v[16:17], v[150:151], 1, v[16:17]
	v_cvt_pk_bf16_f32 v12, v12, v13
	v_cvt_pk_bf16_f32 v13, v14, v15
	v_cvt_pk_bf16_f32 v14, v8, v9
	v_cvt_pk_bf16_f32 v15, v10, v11
	s_and_b64 vcc, exec, s[40:41]
	global_store_dwordx4 v[16:17], v[12:15], off
	s_cbranch_vccnz .LBB0_371
	v_pk_mul_f32 v[4:5], v[4:5], s[90:91] op_sel:[0,1]
	v_pk_mul_f32 v[0:1], v[0:1], s[90:91] op_sel:[0,1]
	v_pk_mul_f32 v[6:7], v[6:7], s[90:91] op_sel:[0,1]
	v_pk_mul_f32 v[2:3], v[2:3], s[90:91] op_sel:[0,1]
	v_exp_f32_e32 v4, v4
	v_exp_f32_e32 v0, v0
	v_exp_f32_e32 v5, v5
	v_exp_f32_e32 v1, v1
	v_exp_f32_e32 v6, v6
	v_exp_f32_e32 v2, v2
	v_exp_f32_e32 v7, v7
	v_exp_f32_e32 v3, v3
	v_pk_add_f32 v[4:5], v[4:5], 1.0 op_sel_hi:[1,0]
	v_pk_add_f32 v[0:1], v[0:1], 1.0 op_sel_hi:[1,0]
	v_pk_add_f32 v[6:7], v[6:7], 1.0 op_sel_hi:[1,0]
	v_pk_add_f32 v[2:3], v[2:3], 1.0 op_sel_hi:[1,0]
	v_rcp_f32_e32 v4, v4
	v_rcp_f32_e32 v0, v0
	v_rcp_f32_e32 v5, v5
	v_rcp_f32_e32 v1, v1
	v_rcp_f32_e32 v6, v6
	v_rcp_f32_e32 v2, v2
	v_rcp_f32_e32 v7, v7
	v_rcp_f32_e32 v3, v3
